# P0: W_in transposes of workgroups 192..255 software-pipelined (two items' loads in flight, LDS reads issued back to back); adaLN GEMV: the 16 serialized silu(c) staging loads issued up front before th
# speedup vs baseline: 1.0103x; 1.0103x over previous
; #define LAS __attribute__((address_space(3)))
; __device__ __forceinline__ int win_src(int p0) {
;     const int pn = p0 >> 8, c = p0 & 255, bj = c >> 7, wc = (c & 127) >> 5;
;     if (pn < 6) return (pn >> 1) * 512 + (4 * (pn & 1) + wc) * 64 + 32 * bj;
;     if (pn < 10) return (bj == 0 ? 1544 : 2568) + 128 * (pn - 6) + (c & 127);
;     return 2056 + 256 * (pn - 10) + c;
; }
; __device__ __forceinline__ void transposes(const Params& p, LAS unsigned char* lds, int it_begin, int it_end, int gw, int NGW, int lane, int wave) {
;     LAS float* scr = (LAS float*)(lds + wave * 8704);
;     constexpr int I_IN = 16 * 96, I_OUT = 16 * 32, I_UP = 16 * 176;
;     for (int it = it_begin + gw; it < it_end; it += NGW) {
;         int r = it;
;         if (r < I_IN) { const int kb = r / 96, nb = r % 96; transpose_item(p.w_in, DIN, 1024, (bf16_t*)(p.ws + WS_WIN), 32 * nb, win_src(32 * nb), 64 * kb, scr, lane); continue; } r -= I_IN;
.LBB0_6:
	s_or_b64 exec, exec, s[6:7]
	s_load_dwordx2 s[4:5], s[96:97], 0
	s_load_dwordx2 s[6:7], s[96:97], 8
	s_load_dwordx2 s[14:15], s[96:97], 16
	s_load_dwordx2 s[12:13], s[96:97], 24
	s_load_dwordx2 s[8:9], s[96:97], 32
	s_load_dwordx2 s[18:19], s[96:97], 40
	s_load_dwordx2 s[10:11], s[96:97], 48
	s_load_dwordx2 s[20:21], s[96:97], 56
	s_load_dwordx2 s[22:23], s[96:97], 64
	s_load_dwordx2 s[28:29], s[96:97], 72
	s_load_dwordx2 s[30:31], s[96:97], 80
	s_load_dwordx2 s[34:35], s[96:97], 88
	s_load_dwordx2 s[36:37], s[96:97], 96
	s_load_dwordx2 s[38:39], s[96:97], 104
	s_load_dwordx2 s[40:41], s[96:97], 112
	s_load_dwordx2 s[42:43], s[96:97], 120
	s_load_dwordx2 s[16:17], s[96:97], 128
	s_waitcnt lgkmcnt(0)
	s_lshr_b32 s58, s3, 6
	s_min_u32 s4, s26, 0xc0
	v_and_b32_e32 v154, 63, v208
	s_cmp_ge_u32 s2, s4
	s_mov_b64 s[8:9], -1
	s_cbranch_scc0 .LBB0_19
	s_lshl_b32 s0, s2, 3
	s_add_i32 s0, s0, s58
	s_add_i32 s5, s0, 0xfffffa00
	s_cmpk_gt_i32 s5, 0x5ff
	s_cbranch_scc1 .LBB0_18
	s_lshl_b32 s22, s26, 3
	s_mul_i32 s0, s58, 0x2200
	v_lshlrev_b32_e32 v3, 3, v208
	s_addk_i32 s22, 0xfa00
	s_add_i32 s0, s0, 0
	v_lshrrev_b32_e32 v2, 3, v154
	v_and_b32_e32 v3, 56, v3
	v_lshrrev_b32_e32 v4, 5, v154
	v_and_b32_e32 v0, 31, v208
	v_mul_u32_u24_e32 v3, 0x84, v3
	v_lshlrev_b32_e32 v5, 2, v2
	s_add_u32 s8, s16, 0x600000
	v_lshl_add_u32 v7, v0, 2, s0
	v_mul_u32_u24_e32 v8, 0x84, v4
	v_add3_u32 v5, s0, v3, v5
	s_addc_u32 s0, s17, 0
	v_lshlrev_b32_e32 v2, 11, v2
	v_and_b32_e32 v3, 7, v208
	s_and_b32 s9, s0, 0xffff
	v_lshl_or_b32 v2, s5, 16, v2
	v_lshlrev_b32_e32 v3, 4, v3
	s_mov_b32 s0, 0xc000
	v_add_u32_e32 v7, v7, v8
	v_mov_b32_e32 v1, 0
	s_mov_b32 s11, 0x20000
	s_brev_b32 s10, -2
	v_or3_b32 v6, v2, v3, s0
	s_lshl_b32 s23, s22, 16
	s_lshl_b32 s28, s5, 5
	s_lshl_b32 s29, s22, 5
	s_movk_i32 s30, 0x608
	s_movk_i32 s31, 0x3020
	v_mov_b64_e32 v[2:3], s[18:19]
	v_lshlrev_b32_e32 v0, 2, v0
	v_add_u32_e32 v8, 0x400, v7
	v_add_u32_e32 v9, 0x800, v7
	v_add_u32_e32 v10, 0xc00, v7
	v_add_u32_e32 v11, 0x1000, v7
	v_add_u32_e32 v12, 0x1400, v7
	v_add_u32_e32 v13, 0x1800, v7
	v_add_u32_e32 v14, 0x1c00, v7
	s_cmpk_lg_i32 s26, 0x100
	s_cbranch_scc1 .LBB0_10
	v_readfirstlane_b32 s38, v2
	v_readfirstlane_b32 s39, v3
	v_mul_u32_u24_e32 v15, 0x3020, v4
	v_add_u32_e32 v15, v15, v0
	s_add_i32 s40, s5, 0
	s_lshl_b32 s41, s40, 5
	s_mul_hi_i32 s42, s40, 0x2aaaaaab
	s_lshr_b32 s43, s42, 31
	s_ashr_i32 s50, s42, 4
	s_add_i32 s50, s50, s43
	s_mul_i32 s42, s50, 0xffffffa0
	s_mul_i32 s43, s50, 0xfffff400
	s_add_i32 s42, s40, s42
	s_add_i32 s44, s41, s43
	s_ashr_i32 s45, s42, 3
	s_and_b32 s46, s44, 0x60
	s_cmp_gt_i32 s45, 5
	s_cbranch_scc0 .Lp0h_low0
	s_and_b32 s47, s44, 0xe0
	s_cmp_gt_u32 s45, 9
	s_cbranch_scc0 .Lp0h_mid0
	s_and_b32 s48, s44, 0xffffff00
	s_or_b32 s48, s48, s47
	s_add_i32 s53, s48, 0xfffffe08
	s_branch .Lp0h_done0
.Lp0h_mid0:
	s_cmpk_lt_u32 s47, 0x80
	s_cselect_b32 s48, s30, 0xa08
	s_lshl_b32 s49, s45, 7
	s_or_b32 s49, s49, s46
	s_add_i32 s48, s49, s48
	s_add_i32 s53, s48, 0xfffffd00
	s_branch .Lp0h_done0
.Lp0h_low0:
	s_lshl_b32 s48, s45, 2
	s_lshr_b32 s49, s46, 5
	s_and_b32 s48, s48, 4
	s_or_b32 s49, s48, s49
	s_and_b32 s48, s44, 0xfffffe00
	s_lshl_b32 s49, s49, 6
	s_or_b32 s49, s49, s48
	s_lshr_b32 s48, s44, 2
	s_and_b32 s48, s48, 32
	s_or_b32 s53, s49, s48
.Lp0h_done0:
	s_add_i32 s40, s5, 512
	s_lshl_b32 s41, s40, 5
	s_mul_hi_i32 s42, s40, 0x2aaaaaab
	s_lshr_b32 s43, s42, 31
	s_ashr_i32 s51, s42, 4
	s_add_i32 s51, s51, s43
	s_mul_i32 s42, s51, 0xffffffa0
	s_mul_i32 s43, s51, 0xfffff400
	s_add_i32 s42, s40, s42
	s_add_i32 s44, s41, s43
	s_ashr_i32 s45, s42, 3
	s_and_b32 s46, s44, 0x60
	s_cmp_gt_i32 s45, 5
	s_cbranch_scc0 .Lp0h_low1
	s_and_b32 s47, s44, 0xe0
	s_cmp_gt_u32 s45, 9
	s_cbranch_scc0 .Lp0h_mid1
	s_and_b32 s48, s44, 0xffffff00
	s_or_b32 s48, s48, s47
	s_add_i32 s54, s48, 0xfffffe08
	s_branch .Lp0h_done1
.Lp0h_mid1:
	s_cmpk_lt_u32 s47, 0x80
	s_cselect_b32 s48, s30, 0xa08
	s_lshl_b32 s49, s45, 7
	s_or_b32 s49, s49, s46
	s_add_i32 s48, s49, s48
	s_add_i32 s54, s48, 0xfffffd00
	s_branch .Lp0h_done1
.Lp0h_low1:
	s_lshl_b32 s48, s45, 2
	s_lshr_b32 s49, s46, 5
	s_and_b32 s48, s48, 4
	s_or_b32 s49, s48, s49
	s_and_b32 s48, s44, 0xfffffe00
	s_lshl_b32 s49, s49, 6
	s_or_b32 s49, s49, s48
	s_lshr_b32 s48, s44, 2
	s_and_b32 s48, s48, 32
	s_or_b32 s54, s49, s48
.Lp0h_done1:
	s_add_i32 s40, s5, 1024
	s_lshl_b32 s41, s40, 5
	s_mul_hi_i32 s42, s40, 0x2aaaaaab
	s_lshr_b32 s43, s42, 31
	s_ashr_i32 s52, s42, 4
	s_add_i32 s52, s52, s43
	s_mul_i32 s42, s52, 0xffffffa0
	s_mul_i32 s43, s52, 0xfffff400
	s_add_i32 s42, s40, s42
	s_add_i32 s44, s41, s43
	s_ashr_i32 s45, s42, 3
	s_and_b32 s46, s44, 0x60
	s_cmp_gt_i32 s45, 5
	s_cbranch_scc0 .Lp0h_low2
	s_and_b32 s47, s44, 0xe0
	s_cmp_gt_u32 s45, 9
	s_cbranch_scc0 .Lp0h_mid2
	s_and_b32 s48, s44, 0xffffff00
	s_or_b32 s48, s48, s47
	s_add_i32 s55, s48, 0xfffffe08
	s_branch .Lp0h_done2
.Lp0h_mid2:
	s_cmpk_lt_u32 s47, 0x80
	s_cselect_b32 s48, s30, 0xa08
	s_lshl_b32 s49, s45, 7
	s_or_b32 s49, s49, s46
	s_add_i32 s48, s49, s48
	s_add_i32 s55, s48, 0xfffffd00
	s_branch .Lp0h_done2
.Lp0h_low2:
	s_lshl_b32 s48, s45, 2
	s_lshr_b32 s49, s46, 5
	s_and_b32 s48, s48, 4
	s_or_b32 s49, s48, s49
	s_and_b32 s48, s44, 0xfffffe00
	s_lshl_b32 s49, s49, 6
	s_or_b32 s49, s49, s48
	s_lshr_b32 s48, s44, 2
	s_and_b32 s48, s48, 32
	s_or_b32 s55, s49, s48
; #define LAS __attribute__((address_space(3)))
; __device__ __forceinline__ void transpose_item(const float* W, int N, int K, bf16_t* WT, int dstrow0, int srccol0, int k0, LAS float* scr, int lane) {
;     float tv[32];
;     { const float* wp = W + (size_t)(k0 + (lane >> 5)) * N + srccol0 + (lane & 31);
; #pragma unroll
;       for (int i = 0; i < 32; ++i) tv[i] = __builtin_nontemporal_load(wp + (size_t)(2 * i) * N); }
.Lp0h_done2:
	s_mul_i32 s66, s50, 0xc0800
	s_lshl_b32 s67, s53, 2
	s_add_u32 s66, s66, s67
	s_add_u32 s64, s38, s66
	s_addc_u32 s65, s39, 0
	global_load_dword v20, v15, s[64:65] nt
	s_add_u32 s64, s64, 0x6040
	s_addc_u32 s65, s65, 0
	global_load_dword v21, v15, s[64:65] nt
	s_add_u32 s64, s64, 0x6040
	s_addc_u32 s65, s65, 0
	global_load_dword v22, v15, s[64:65] nt
	s_add_u32 s64, s64, 0x6040
	s_addc_u32 s65, s65, 0
	global_load_dword v23, v15, s[64:65] nt
	s_add_u32 s64, s64, 0x6040
	s_addc_u32 s65, s65, 0
	global_load_dword v24, v15, s[64:65] nt
	s_add_u32 s64, s64, 0x6040
	s_addc_u32 s65, s65, 0
	global_load_dword v25, v15, s[64:65] nt
	s_add_u32 s64, s64, 0x6040
	s_addc_u32 s65, s65, 0
	global_load_dword v26, v15, s[64:65] nt
	s_add_u32 s64, s64, 0x6040
	s_addc_u32 s65, s65, 0
	global_load_dword v27, v15, s[64:65] nt
	s_add_u32 s64, s64, 0x6040
	s_addc_u32 s65, s65, 0
	global_load_dword v28, v15, s[64:65] nt
	s_add_u32 s64, s64, 0x6040
	s_addc_u32 s65, s65, 0
	global_load_dword v29, v15, s[64:65] nt
	s_add_u32 s64, s64, 0x6040
	s_addc_u32 s65, s65, 0
	global_load_dword v30, v15, s[64:65] nt
	s_add_u32 s64, s64, 0x6040
	s_addc_u32 s65, s65, 0
	global_load_dword v31, v15, s[64:65] nt
	s_add_u32 s64, s64, 0x6040
	s_addc_u32 s65, s65, 0
	global_load_dword v32, v15, s[64:65] nt
	s_add_u32 s64, s64, 0x6040
	s_addc_u32 s65, s65, 0
	global_load_dword v33, v15, s[64:65] nt
	s_add_u32 s64, s64, 0x6040
	s_addc_u32 s65, s65, 0
	global_load_dword v34, v15, s[64:65] nt
	s_add_u32 s64, s64, 0x6040
	s_addc_u32 s65, s65, 0
	global_load_dword v35, v15, s[64:65] nt
	s_add_u32 s64, s64, 0x6040
	s_addc_u32 s65, s65, 0
	global_load_dword v36, v15, s[64:65] nt
	s_add_u32 s64, s64, 0x6040
	s_addc_u32 s65, s65, 0
	global_load_dword v37, v15, s[64:65] nt
	s_add_u32 s64, s64, 0x6040
	s_addc_u32 s65, s65, 0
	global_load_dword v38, v15, s[64:65] nt
	s_add_u32 s64, s64, 0x6040
	s_addc_u32 s65, s65, 0
	global_load_dword v39, v15, s[64:65] nt
	s_add_u32 s64, s64, 0x6040
	s_addc_u32 s65, s65, 0
	global_load_dword v40, v15, s[64:65] nt
	s_add_u32 s64, s64, 0x6040
	s_addc_u32 s65, s65, 0
	global_load_dword v41, v15, s[64:65] nt
	s_add_u32 s64, s64, 0x6040
	s_addc_u32 s65, s65, 0
	global_load_dword v42, v15, s[64:65] nt
	s_add_u32 s64, s64, 0x6040
	s_addc_u32 s65, s65, 0
	global_load_dword v43, v15, s[64:65] nt
	s_add_u32 s64, s64, 0x6040
	s_addc_u32 s65, s65, 0
	global_load_dword v44, v15, s[64:65] nt
	s_add_u32 s64, s64, 0x6040
	s_addc_u32 s65, s65, 0
	global_load_dword v45, v15, s[64:65] nt
	s_add_u32 s64, s64, 0x6040
	s_addc_u32 s65, s65, 0
	global_load_dword v46, v15, s[64:65] nt
	s_add_u32 s64, s64, 0x6040
	s_addc_u32 s65, s65, 0
	global_load_dword v47, v15, s[64:65] nt
	s_add_u32 s64, s64, 0x6040
	s_addc_u32 s65, s65, 0
	global_load_dword v48, v15, s[64:65] nt
	s_add_u32 s64, s64, 0x6040
	s_addc_u32 s65, s65, 0
	global_load_dword v49, v15, s[64:65] nt
	s_add_u32 s64, s64, 0x6040
	s_addc_u32 s65, s65, 0
	global_load_dword v50, v15, s[64:65] nt
	s_add_u32 s64, s64, 0x6040
	s_addc_u32 s65, s65, 0
	global_load_dword v51, v15, s[64:65] nt
	s_mul_i32 s66, s51, 0xc0800
	s_lshl_b32 s67, s54, 2
	s_add_u32 s66, s66, s67
	s_add_u32 s64, s38, s66
	s_addc_u32 s65, s39, 0
	global_load_dword v52, v15, s[64:65] nt
	s_add_u32 s64, s64, 0x6040
	s_addc_u32 s65, s65, 0
	global_load_dword v53, v15, s[64:65] nt
	s_add_u32 s64, s64, 0x6040
	s_addc_u32 s65, s65, 0
	global_load_dword v54, v15, s[64:65] nt
	s_add_u32 s64, s64, 0x6040
	s_addc_u32 s65, s65, 0
	global_load_dword v55, v15, s[64:65] nt
	s_add_u32 s64, s64, 0x6040
	s_addc_u32 s65, s65, 0
	global_load_dword v56, v15, s[64:65] nt
	s_add_u32 s64, s64, 0x6040
	s_addc_u32 s65, s65, 0
	global_load_dword v57, v15, s[64:65] nt
	s_add_u32 s64, s64, 0x6040
	s_addc_u32 s65, s65, 0
	global_load_dword v58, v15, s[64:65] nt
	s_add_u32 s64, s64, 0x6040
	s_addc_u32 s65, s65, 0
	global_load_dword v59, v15, s[64:65] nt
	s_add_u32 s64, s64, 0x6040
	s_addc_u32 s65, s65, 0
	global_load_dword v60, v15, s[64:65] nt
	s_add_u32 s64, s64, 0x6040
	s_addc_u32 s65, s65, 0
	global_load_dword v61, v15, s[64:65] nt
	s_add_u32 s64, s64, 0x6040
	s_addc_u32 s65, s65, 0
	global_load_dword v62, v15, s[64:65] nt
	s_add_u32 s64, s64, 0x6040
	s_addc_u32 s65, s65, 0
	global_load_dword v63, v15, s[64:65] nt
	s_add_u32 s64, s64, 0x6040
	s_addc_u32 s65, s65, 0
	global_load_dword v64, v15, s[64:65] nt
	s_add_u32 s64, s64, 0x6040
	s_addc_u32 s65, s65, 0
	global_load_dword v65, v15, s[64:65] nt
	s_add_u32 s64, s64, 0x6040
	s_addc_u32 s65, s65, 0
	global_load_dword v66, v15, s[64:65] nt
	s_add_u32 s64, s64, 0x6040
	s_addc_u32 s65, s65, 0
	global_load_dword v67, v15, s[64:65] nt
	s_add_u32 s64, s64, 0x6040
	s_addc_u32 s65, s65, 0
	global_load_dword v68, v15, s[64:65] nt
	s_add_u32 s64, s64, 0x6040
	s_addc_u32 s65, s65, 0
	global_load_dword v69, v15, s[64:65] nt
	s_add_u32 s64, s64, 0x6040
	s_addc_u32 s65, s65, 0
	global_load_dword v70, v15, s[64:65] nt
	s_add_u32 s64, s64, 0x6040
	s_addc_u32 s65, s65, 0
	global_load_dword v71, v15, s[64:65] nt
	s_add_u32 s64, s64, 0x6040
	s_addc_u32 s65, s65, 0
	global_load_dword v72, v15, s[64:65] nt
	s_add_u32 s64, s64, 0x6040
	s_addc_u32 s65, s65, 0
	global_load_dword v73, v15, s[64:65] nt
	s_add_u32 s64, s64, 0x6040
	s_addc_u32 s65, s65, 0
	global_load_dword v74, v15, s[64:65] nt
	s_add_u32 s64, s64, 0x6040
	s_addc_u32 s65, s65, 0
	global_load_dword v75, v15, s[64:65] nt
	s_add_u32 s64, s64, 0x6040
	s_addc_u32 s65, s65, 0
	global_load_dword v76, v15, s[64:65] nt
	s_add_u32 s64, s64, 0x6040
	s_addc_u32 s65, s65, 0
	global_load_dword v77, v15, s[64:65] nt
	s_add_u32 s64, s64, 0x6040
	s_addc_u32 s65, s65, 0
	global_load_dword v78, v15, s[64:65] nt
	s_add_u32 s64, s64, 0x6040
	s_addc_u32 s65, s65, 0
	global_load_dword v79, v15, s[64:65] nt
	s_add_u32 s64, s64, 0x6040
	s_addc_u32 s65, s65, 0
	global_load_dword v80, v15, s[64:65] nt
	s_add_u32 s64, s64, 0x6040
	s_addc_u32 s65, s65, 0
	global_load_dword v81, v15, s[64:65] nt
	s_add_u32 s64, s64, 0x6040
	s_addc_u32 s65, s65, 0
	global_load_dword v82, v15, s[64:65] nt
	s_add_u32 s64, s64, 0x6040
	s_addc_u32 s65, s65, 0
	global_load_dword v83, v15, s[64:65] nt
	s_waitcnt vmcnt(62)
; #define LAS __attribute__((address_space(3)))
; __device__ __forceinline__ unsigned pk2(float lo, float hi) { return pg8::cvt_pk_bf16(lo, hi); }
; __device__ __forceinline__ void transpose_item(const float* W, int N, int K, bf16_t* WT, int dstrow0, int srccol0, int k0, LAS float* scr, int lane) {
;     ...
;       for (int i = 0; i < 32; ++i) tv[i] = __builtin_nontemporal_load(wp + (size_t)(2 * i) * N); }
; #pragma unroll
;     for (int i = 0; i < 32; ++i) scr[(2 * i + (lane >> 5)) * 33 + (lane & 31)] = tv[i];
;     asm volatile("s_waitcnt lgkmcnt(0)" ::: "memory");
;     const int c = lane & 7;
; #pragma unroll
;     for (int j = 0; j < 4; ++j) { const int n = (lane >> 3) + 8 * j; const LAS float* s = scr + (8 * c) * 33 + n;
;         u32x4 o; o.x = pk2(s[0 * 33], s[1 * 33]); o.y = pk2(s[2 * 33], s[3 * 33]); o.z = pk2(s[4 * 33], s[5 * 33]); o.w = pk2(s[6 * 33], s[7 * 33]);
;         st16wt(WT, (unsigned)(((dstrow0 + n) * K + k0 + 8 * c) * 2), o); }
;     asm volatile("s_waitcnt lgkmcnt(0)" ::: "memory");
	ds_write2_b32 v7, v20, v21 offset1:66
	s_waitcnt vmcnt(60)
	ds_write2_b32 v7, v22, v23 offset0:132 offset1:198
	s_waitcnt vmcnt(58)
	ds_write2_b32 v8, v24, v25 offset0:8 offset1:74
	s_waitcnt vmcnt(56)
	ds_write2_b32 v8, v26, v27 offset0:140 offset1:206
	s_waitcnt vmcnt(54)
	ds_write2_b32 v9, v28, v29 offset0:16 offset1:82
	s_waitcnt vmcnt(52)
	ds_write2_b32 v9, v30, v31 offset0:148 offset1:214
	s_waitcnt vmcnt(50)
	ds_write2_b32 v10, v32, v33 offset0:24 offset1:90
	s_waitcnt vmcnt(48)
	ds_write2_b32 v10, v34, v35 offset0:156 offset1:222
	s_waitcnt vmcnt(46)
	ds_write2_b32 v11, v36, v37 offset0:32 offset1:98
	s_waitcnt vmcnt(44)
	ds_write2_b32 v11, v38, v39 offset0:164 offset1:230
	s_waitcnt vmcnt(42)
	ds_write2_b32 v12, v40, v41 offset0:40 offset1:106
	s_waitcnt vmcnt(40)
	ds_write2_b32 v12, v42, v43 offset0:172 offset1:238
	s_waitcnt vmcnt(38)
	ds_write2_b32 v13, v44, v45 offset0:48 offset1:114
	s_waitcnt vmcnt(36)
	ds_write2_b32 v13, v46, v47 offset0:180 offset1:246
	s_waitcnt vmcnt(34)
	ds_write2_b32 v14, v48, v49 offset0:56 offset1:122
	s_waitcnt vmcnt(32)
	ds_write2_b32 v14, v50, v51 offset0:188 offset1:254
	s_waitcnt lgkmcnt(0)
	s_mul_i32 s66, s52, 0xc0800
	s_lshl_b32 s67, s55, 2
	s_add_u32 s66, s66, s67
	s_add_u32 s64, s38, s66
	s_addc_u32 s65, s39, 0
	global_load_dword v20, v15, s[64:65] nt
	s_add_u32 s64, s64, 0x6040
	s_addc_u32 s65, s65, 0
	global_load_dword v21, v15, s[64:65] nt
	s_add_u32 s64, s64, 0x6040
	s_addc_u32 s65, s65, 0
	global_load_dword v22, v15, s[64:65] nt
	s_add_u32 s64, s64, 0x6040
	s_addc_u32 s65, s65, 0
	global_load_dword v23, v15, s[64:65] nt
	s_add_u32 s64, s64, 0x6040
	s_addc_u32 s65, s65, 0
	global_load_dword v24, v15, s[64:65] nt
	s_add_u32 s64, s64, 0x6040
	s_addc_u32 s65, s65, 0
	global_load_dword v25, v15, s[64:65] nt
	s_add_u32 s64, s64, 0x6040
	s_addc_u32 s65, s65, 0
	global_load_dword v26, v15, s[64:65] nt
	s_add_u32 s64, s64, 0x6040
	s_addc_u32 s65, s65, 0
	global_load_dword v27, v15, s[64:65] nt
	s_add_u32 s64, s64, 0x6040
	s_addc_u32 s65, s65, 0
	global_load_dword v28, v15, s[64:65] nt
	s_add_u32 s64, s64, 0x6040
	s_addc_u32 s65, s65, 0
	global_load_dword v29, v15, s[64:65] nt
	s_add_u32 s64, s64, 0x6040
	s_addc_u32 s65, s65, 0
	global_load_dword v30, v15, s[64:65] nt
	s_add_u32 s64, s64, 0x6040
	s_addc_u32 s65, s65, 0
	global_load_dword v31, v15, s[64:65] nt
	s_add_u32 s64, s64, 0x6040
	s_addc_u32 s65, s65, 0
	global_load_dword v32, v15, s[64:65] nt
	s_add_u32 s64, s64, 0x6040
	s_addc_u32 s65, s65, 0
	global_load_dword v33, v15, s[64:65] nt
	s_add_u32 s64, s64, 0x6040
	s_addc_u32 s65, s65, 0
	global_load_dword v34, v15, s[64:65] nt
	s_add_u32 s64, s64, 0x6040
	s_addc_u32 s65, s65, 0
	global_load_dword v35, v15, s[64:65] nt
	s_add_u32 s64, s64, 0x6040
	s_addc_u32 s65, s65, 0
	global_load_dword v36, v15, s[64:65] nt
	s_add_u32 s64, s64, 0x6040
	s_addc_u32 s65, s65, 0
	global_load_dword v37, v15, s[64:65] nt
	s_add_u32 s64, s64, 0x6040
	s_addc_u32 s65, s65, 0
	global_load_dword v38, v15, s[64:65] nt
	s_add_u32 s64, s64, 0x6040
	s_addc_u32 s65, s65, 0
	global_load_dword v39, v15, s[64:65] nt
	s_add_u32 s64, s64, 0x6040
	s_addc_u32 s65, s65, 0
	global_load_dword v40, v15, s[64:65] nt
	s_add_u32 s64, s64, 0x6040
	s_addc_u32 s65, s65, 0
	global_load_dword v41, v15, s[64:65] nt
	s_add_u32 s64, s64, 0x6040
	s_addc_u32 s65, s65, 0
	global_load_dword v42, v15, s[64:65] nt
	s_add_u32 s64, s64, 0x6040
	s_addc_u32 s65, s65, 0
	global_load_dword v43, v15, s[64:65] nt
	s_add_u32 s64, s64, 0x6040
	s_addc_u32 s65, s65, 0
	global_load_dword v44, v15, s[64:65] nt
	s_add_u32 s64, s64, 0x6040
	s_addc_u32 s65, s65, 0
	global_load_dword v45, v15, s[64:65] nt
	s_add_u32 s64, s64, 0x6040
	s_addc_u32 s65, s65, 0
	global_load_dword v46, v15, s[64:65] nt
	s_add_u32 s64, s64, 0x6040
	s_addc_u32 s65, s65, 0
	global_load_dword v47, v15, s[64:65] nt
	s_add_u32 s64, s64, 0x6040
	s_addc_u32 s65, s65, 0
	global_load_dword v48, v15, s[64:65] nt
	s_add_u32 s64, s64, 0x6040
	s_addc_u32 s65, s65, 0
	global_load_dword v49, v15, s[64:65] nt
	s_add_u32 s64, s64, 0x6040
	s_addc_u32 s65, s65, 0
	global_load_dword v50, v15, s[64:65] nt
	s_add_u32 s64, s64, 0x6040
	s_addc_u32 s65, s65, 0
	global_load_dword v51, v15, s[64:65] nt
	s_mul_i32 s66, s50, 0xffa00080
	v_add_u32_e32 v176, s66, v6
	v_add_u32_e32 v177, 0xffff4000, v176
	v_add_u32_e32 v178, 0xffff8000, v176
	v_add_u32_e32 v179, 0xffffc000, v176
	ds_read2_b32 v[120:121], v5 offset1:33
	ds_read2_b32 v[122:123], v5 offset0:66 offset1:99
	ds_read2_b32 v[124:125], v5 offset0:132 offset1:165
	ds_read2_b32 v[126:127], v5 offset0:198 offset1:231
	ds_read2_b32 v[128:129], v5 offset0:8 offset1:41
	ds_read2_b32 v[130:131], v5 offset0:74 offset1:107
	ds_read2_b32 v[132:133], v5 offset0:140 offset1:173
	ds_read2_b32 v[134:135], v5 offset0:206 offset1:239
	ds_read2_b32 v[136:137], v5 offset0:16 offset1:49
	ds_read2_b32 v[138:139], v5 offset0:82 offset1:115
	ds_read2_b32 v[140:141], v5 offset0:148 offset1:181
	ds_read2_b32 v[142:143], v5 offset0:214 offset1:247
	ds_read2_b32 v[144:145], v5 offset0:24 offset1:57
	ds_read2_b32 v[146:147], v5 offset0:90 offset1:123
	ds_read2_b32 v[148:149], v5 offset0:156 offset1:189
	ds_read2_b32 v[150:151], v5 offset0:222 offset1:255
	s_waitcnt lgkmcnt(12)
	v_cvt_pk_bf16_f32 v160, v120, v121
	v_cvt_pk_bf16_f32 v161, v122, v123
	v_cvt_pk_bf16_f32 v162, v124, v125
	v_cvt_pk_bf16_f32 v163, v126, v127
	buffer_store_dwordx4 v[160:163], v177, s[8:11], 0 offen sc1
	s_waitcnt lgkmcnt(8)
	v_cvt_pk_bf16_f32 v164, v128, v129
	v_cvt_pk_bf16_f32 v165, v130, v131
	v_cvt_pk_bf16_f32 v166, v132, v133
	v_cvt_pk_bf16_f32 v167, v134, v135
	buffer_store_dwordx4 v[164:167], v178, s[8:11], 0 offen sc1
	s_waitcnt lgkmcnt(4)
; #define LAS __attribute__((address_space(3)))
; __device__ __forceinline__ unsigned pk2(float lo, float hi) { return pg8::cvt_pk_bf16(lo, hi); }
; __device__ __forceinline__ void transpose_item(const float* W, int N, int K, bf16_t* WT, int dstrow0, int srccol0, int k0, LAS float* scr, int lane) {
;     ...
;     for (int i = 0; i < 32; ++i) scr[(2 * i + (lane >> 5)) * 33 + (lane & 31)] = tv[i];
;     asm volatile("s_waitcnt lgkmcnt(0)" ::: "memory");
;     const int c = lane & 7;
; #pragma unroll
;     for (int j = 0; j < 4; ++j) { const int n = (lane >> 3) + 8 * j; const LAS float* s = scr + (8 * c) * 33 + n;
;         u32x4 o; o.x = pk2(s[0 * 33], s[1 * 33]); o.y = pk2(s[2 * 33], s[3 * 33]); o.z = pk2(s[4 * 33], s[5 * 33]); o.w = pk2(s[6 * 33], s[7 * 33]);
;         st16wt(WT, (unsigned)(((dstrow0 + n) * K + k0 + 8 * c) * 2), o); }
;     asm volatile("s_waitcnt lgkmcnt(0)" ::: "memory");
	v_cvt_pk_bf16_f32 v168, v136, v137
	v_cvt_pk_bf16_f32 v169, v138, v139
	v_cvt_pk_bf16_f32 v170, v140, v141
	v_cvt_pk_bf16_f32 v171, v142, v143
	buffer_store_dwordx4 v[168:171], v179, s[8:11], 0 offen sc1
	s_waitcnt lgkmcnt(0)
	v_cvt_pk_bf16_f32 v172, v144, v145
	v_cvt_pk_bf16_f32 v173, v146, v147
	v_cvt_pk_bf16_f32 v174, v148, v149
	v_cvt_pk_bf16_f32 v175, v150, v151
	buffer_store_dwordx4 v[172:175], v176, s[8:11], 0 offen sc1
	s_waitcnt vmcnt(63)
	ds_write2_b32 v7, v52, v53 offset1:66
	s_waitcnt vmcnt(63)
	ds_write2_b32 v7, v54, v55 offset0:132 offset1:198
	s_waitcnt vmcnt(62)
	ds_write2_b32 v8, v56, v57 offset0:8 offset1:74
	s_waitcnt vmcnt(60)
	ds_write2_b32 v8, v58, v59 offset0:140 offset1:206
	s_waitcnt vmcnt(58)
	ds_write2_b32 v9, v60, v61 offset0:16 offset1:82
	s_waitcnt vmcnt(56)
	ds_write2_b32 v9, v62, v63 offset0:148 offset1:214
	s_waitcnt vmcnt(54)
	ds_write2_b32 v10, v64, v65 offset0:24 offset1:90
	s_waitcnt vmcnt(52)
	ds_write2_b32 v10, v66, v67 offset0:156 offset1:222
	s_waitcnt vmcnt(50)
	ds_write2_b32 v11, v68, v69 offset0:32 offset1:98
	s_waitcnt vmcnt(48)
	ds_write2_b32 v11, v70, v71 offset0:164 offset1:230
	s_waitcnt vmcnt(46)
	ds_write2_b32 v12, v72, v73 offset0:40 offset1:106
	s_waitcnt vmcnt(44)
	ds_write2_b32 v12, v74, v75 offset0:172 offset1:238
	s_waitcnt vmcnt(42)
	ds_write2_b32 v13, v76, v77 offset0:48 offset1:114
	s_waitcnt vmcnt(40)
	ds_write2_b32 v13, v78, v79 offset0:180 offset1:246
	s_waitcnt vmcnt(38)
	ds_write2_b32 v14, v80, v81 offset0:56 offset1:122
	s_waitcnt vmcnt(36)
	ds_write2_b32 v14, v82, v83 offset0:188 offset1:254
	s_waitcnt lgkmcnt(0)
	s_mul_i32 s66, s51, 0xffa00080
	s_add_i32 s66, s66, 0x2000000
	v_add_u32_e32 v176, s66, v6
	v_add_u32_e32 v177, 0xffff4000, v176
	v_add_u32_e32 v178, 0xffff8000, v176
	v_add_u32_e32 v179, 0xffffc000, v176
	ds_read2_b32 v[120:121], v5 offset1:33
	ds_read2_b32 v[122:123], v5 offset0:66 offset1:99
	ds_read2_b32 v[124:125], v5 offset0:132 offset1:165
	ds_read2_b32 v[126:127], v5 offset0:198 offset1:231
	ds_read2_b32 v[128:129], v5 offset0:8 offset1:41
	ds_read2_b32 v[130:131], v5 offset0:74 offset1:107
	ds_read2_b32 v[132:133], v5 offset0:140 offset1:173
	ds_read2_b32 v[134:135], v5 offset0:206 offset1:239
	ds_read2_b32 v[136:137], v5 offset0:16 offset1:49
	ds_read2_b32 v[138:139], v5 offset0:82 offset1:115
	ds_read2_b32 v[140:141], v5 offset0:148 offset1:181
	ds_read2_b32 v[142:143], v5 offset0:214 offset1:247
	ds_read2_b32 v[144:145], v5 offset0:24 offset1:57
	ds_read2_b32 v[146:147], v5 offset0:90 offset1:123
	ds_read2_b32 v[148:149], v5 offset0:156 offset1:189
	ds_read2_b32 v[150:151], v5 offset0:222 offset1:255
	s_waitcnt lgkmcnt(12)
	v_cvt_pk_bf16_f32 v160, v120, v121
	v_cvt_pk_bf16_f32 v161, v122, v123
	v_cvt_pk_bf16_f32 v162, v124, v125
	v_cvt_pk_bf16_f32 v163, v126, v127
	buffer_store_dwordx4 v[160:163], v177, s[8:11], 0 offen sc1
	s_waitcnt lgkmcnt(8)
	v_cvt_pk_bf16_f32 v164, v128, v129
	v_cvt_pk_bf16_f32 v165, v130, v131
	v_cvt_pk_bf16_f32 v166, v132, v133
	v_cvt_pk_bf16_f32 v167, v134, v135
	buffer_store_dwordx4 v[164:167], v178, s[8:11], 0 offen sc1
	s_waitcnt lgkmcnt(4)
	v_cvt_pk_bf16_f32 v168, v136, v137
	v_cvt_pk_bf16_f32 v169, v138, v139
	v_cvt_pk_bf16_f32 v170, v140, v141
	v_cvt_pk_bf16_f32 v171, v142, v143
	buffer_store_dwordx4 v[168:171], v179, s[8:11], 0 offen sc1
	s_waitcnt lgkmcnt(0)
	v_cvt_pk_bf16_f32 v172, v144, v145
	v_cvt_pk_bf16_f32 v173, v146, v147
	v_cvt_pk_bf16_f32 v174, v148, v149
	v_cvt_pk_bf16_f32 v175, v150, v151
	buffer_store_dwordx4 v[172:175], v176, s[8:11], 0 offen sc1
	s_waitcnt vmcnt(38)
	ds_write2_b32 v7, v20, v21 offset1:66
	s_waitcnt vmcnt(36)
	ds_write2_b32 v7, v22, v23 offset0:132 offset1:198
	s_waitcnt vmcnt(34)
	ds_write2_b32 v8, v24, v25 offset0:8 offset1:74
	s_waitcnt vmcnt(32)
	ds_write2_b32 v8, v26, v27 offset0:140 offset1:206
	s_waitcnt vmcnt(30)
	ds_write2_b32 v9, v28, v29 offset0:16 offset1:82
	s_waitcnt vmcnt(28)
	ds_write2_b32 v9, v30, v31 offset0:148 offset1:214
	s_waitcnt vmcnt(26)
	ds_write2_b32 v10, v32, v33 offset0:24 offset1:90
	s_waitcnt vmcnt(24)
	ds_write2_b32 v10, v34, v35 offset0:156 offset1:222
	s_waitcnt vmcnt(22)
	ds_write2_b32 v11, v36, v37 offset0:32 offset1:98
	s_waitcnt vmcnt(20)
	ds_write2_b32 v11, v38, v39 offset0:164 offset1:230
	s_waitcnt vmcnt(18)
	ds_write2_b32 v12, v40, v41 offset0:40 offset1:106
	s_waitcnt vmcnt(16)
	ds_write2_b32 v12, v42, v43 offset0:172 offset1:238
	s_waitcnt vmcnt(14)
	ds_write2_b32 v13, v44, v45 offset0:48 offset1:114
	s_waitcnt vmcnt(12)
	ds_write2_b32 v13, v46, v47 offset0:180 offset1:246
	s_waitcnt vmcnt(10)
	ds_write2_b32 v14, v48, v49 offset0:56 offset1:122
	s_waitcnt vmcnt(8)
	ds_write2_b32 v14, v50, v51 offset0:188 offset1:254
	s_waitcnt lgkmcnt(0)
	s_mul_i32 s66, s52, 0xffa00080
	s_add_i32 s66, s66, 0x4000000
	v_add_u32_e32 v176, s66, v6
	v_add_u32_e32 v177, 0xffff4000, v176
	v_add_u32_e32 v178, 0xffff8000, v176
	v_add_u32_e32 v179, 0xffffc000, v176
	ds_read2_b32 v[120:121], v5 offset1:33
	ds_read2_b32 v[122:123], v5 offset0:66 offset1:99
	ds_read2_b32 v[124:125], v5 offset0:132 offset1:165
	ds_read2_b32 v[126:127], v5 offset0:198 offset1:231
	ds_read2_b32 v[128:129], v5 offset0:8 offset1:41
	ds_read2_b32 v[130:131], v5 offset0:74 offset1:107
	ds_read2_b32 v[132:133], v5 offset0:140 offset1:173
	ds_read2_b32 v[134:135], v5 offset0:206 offset1:239
	ds_read2_b32 v[136:137], v5 offset0:16 offset1:49
	ds_read2_b32 v[138:139], v5 offset0:82 offset1:115
	ds_read2_b32 v[140:141], v5 offset0:148 offset1:181
	ds_read2_b32 v[142:143], v5 offset0:214 offset1:247
	ds_read2_b32 v[144:145], v5 offset0:24 offset1:57
	ds_read2_b32 v[146:147], v5 offset0:90 offset1:123
	ds_read2_b32 v[148:149], v5 offset0:156 offset1:189
	ds_read2_b32 v[150:151], v5 offset0:222 offset1:255
	s_waitcnt lgkmcnt(12)
	v_cvt_pk_bf16_f32 v160, v120, v121
	v_cvt_pk_bf16_f32 v161, v122, v123
	v_cvt_pk_bf16_f32 v162, v124, v125
	v_cvt_pk_bf16_f32 v163, v126, v127
	buffer_store_dwordx4 v[160:163], v177, s[8:11], 0 offen sc1
	s_waitcnt lgkmcnt(8)
	v_cvt_pk_bf16_f32 v164, v128, v129
	v_cvt_pk_bf16_f32 v165, v130, v131
	v_cvt_pk_bf16_f32 v166, v132, v133
	v_cvt_pk_bf16_f32 v167, v134, v135
	buffer_store_dwordx4 v[164:167], v178, s[8:11], 0 offen sc1
	s_waitcnt lgkmcnt(4)
	v_cvt_pk_bf16_f32 v168, v136, v137
	v_cvt_pk_bf16_f32 v169, v138, v139
	v_cvt_pk_bf16_f32 v170, v140, v141
	v_cvt_pk_bf16_f32 v171, v142, v143
	buffer_store_dwordx4 v[168:171], v179, s[8:11], 0 offen sc1
	s_waitcnt lgkmcnt(0)
	v_cvt_pk_bf16_f32 v172, v144, v145
	v_cvt_pk_bf16_f32 v173, v146, v147
	v_cvt_pk_bf16_f32 v174, v148, v149
	v_cvt_pk_bf16_f32 v175, v150, v151
	buffer_store_dwordx4 v[172:175], v176, s[8:11], 0 offen sc1
	s_branch .LBB0_18

; __device__ __forceinline__ void gemv_load(const float* W, int N, int n0, f32x4 (&wv)[16], int tid) {
;     const int cgp = tid & 7, kg = tid >> 3;
; #pragma unroll
;     for (int i = 0; i < 16; ++i) wv[i] = __builtin_nontemporal_load((const f32x4*)(W + (size_t)(kg + 64 * i) * N + n0 + 4 * cgp));
; }
; __device__ __forceinline__ void phase0(const Params& p, LAS unsigned char* lds, int tid, int lane, int wave) {
;     ...
;         f32x4 wv[16]; gemv_load(p.w_ada, NMOD, 32 * blockIdx.x, wv, tid);
;         for (int i = tid; i < 8192; i += 512) { const float v = p.c[i]; vecs[i] = v / (1.f + __expf(-v)); }
.LBB0_19:
	s_andn2_b64 vcc, exec, s[8:9]
	v_lshrrev_b32_e32 v174, 3, v208
	v_lshlrev_b32_e32 v96, 2, v208
	s_cbranch_vccnz .LBB0_32
	s_mov_b32 s20, s6
	s_mov_b32 s21, s7
	global_load_dword v120, v96, s[20:21]
	s_add_u32 s20, s20, 0x800
	s_addc_u32 s21, s21, 0
	global_load_dword v121, v96, s[20:21]
	s_add_u32 s20, s20, 0x800
	s_addc_u32 s21, s21, 0
	global_load_dword v122, v96, s[20:21]
	s_add_u32 s20, s20, 0x800
	s_addc_u32 s21, s21, 0
	global_load_dword v123, v96, s[20:21]
	s_add_u32 s20, s20, 0x800
	s_addc_u32 s21, s21, 0
	global_load_dword v124, v96, s[20:21]
	s_add_u32 s20, s20, 0x800
	s_addc_u32 s21, s21, 0
	global_load_dword v125, v96, s[20:21]
	s_add_u32 s20, s20, 0x800
	s_addc_u32 s21, s21, 0
	global_load_dword v126, v96, s[20:21]
	s_add_u32 s20, s20, 0x800
	s_addc_u32 s21, s21, 0
	global_load_dword v127, v96, s[20:21]
	s_add_u32 s20, s20, 0x800
	s_addc_u32 s21, s21, 0
	global_load_dword v128, v96, s[20:21]
	s_add_u32 s20, s20, 0x800
	s_addc_u32 s21, s21, 0
	global_load_dword v129, v96, s[20:21]
	s_add_u32 s20, s20, 0x800
	s_addc_u32 s21, s21, 0
	global_load_dword v130, v96, s[20:21]
	s_add_u32 s20, s20, 0x800
	s_addc_u32 s21, s21, 0
	global_load_dword v131, v96, s[20:21]
	s_add_u32 s20, s20, 0x800
	s_addc_u32 s21, s21, 0
	global_load_dword v132, v96, s[20:21]
	s_add_u32 s20, s20, 0x800
	s_addc_u32 s21, s21, 0
	global_load_dword v133, v96, s[20:21]
	s_add_u32 s20, s20, 0x800
	s_addc_u32 s21, s21, 0
	global_load_dword v134, v96, s[20:21]
	s_add_u32 s20, s20, 0x800
	s_addc_u32 s21, s21, 0
	global_load_dword v135, v96, s[20:21]
	s_lshl_b32 s8, s2, 5
	s_mov_b32 s9, 0
	s_lshl_b64 s[10:11], s[8:9], 2
	s_add_u32 s10, s14, s10
	v_and_b32_e32 v66, 28, v96
	s_addc_u32 s11, s15, s11
	v_mov_b32_e32 v71, 0
	v_lshlrev_b32_e32 v70, 2, v66
	v_mul_u32_u24_e32 v64, 0x1800, v174
	v_lshl_add_u64 v[24:25], s[10:11], 0, v[70:71]
	v_lshlrev_b32_e32 v70, 2, v64
	v_lshl_add_u64 v[26:27], v[24:25], 0, v[70:71]
	s_mov_b32 s0, 0x180000
	v_add_co_u32_e32 v8, vcc, s0, v26
	s_mov_b32 s0, 0x300000
	s_nop 0
	v_addc_co_u32_e32 v9, vcc, 0, v27, vcc
	v_add_co_u32_e32 v16, vcc, s0, v26
	s_mov_b32 s0, 0x480000
	s_nop 0
	v_addc_co_u32_e32 v17, vcc, 0, v27, vcc
	v_add_co_u32_e32 v18, vcc, s0, v26
	s_mov_b32 s0, 0x600000
	s_nop 0
	v_addc_co_u32_e32 v19, vcc, 0, v27, vcc
	v_add_co_u32_e32 v28, vcc, s0, v26
	s_mov_b32 s0, 0x780000
	s_nop 0
	v_addc_co_u32_e32 v29, vcc, 0, v27, vcc
	v_add_co_u32_e32 v30, vcc, s0, v26
	s_mov_b32 s0, 0x900000
	s_nop 0
	v_addc_co_u32_e32 v31, vcc, 0, v27, vcc
	v_add_co_u32_e32 v72, vcc, s0, v26
	s_mov_b32 s0, 0xa80000
	s_nop 0
	v_addc_co_u32_e32 v73, vcc, 0, v27, vcc
	v_add_co_u32_e32 v74, vcc, s0, v26
	s_mov_b32 s0, 0xd80000
	s_nop 0
	v_addc_co_u32_e32 v75, vcc, 0, v27, vcc
	v_add_co_u32_e32 v78, vcc, s0, v26
	s_mov_b32 s0, 0xf00000
	s_nop 0
	v_addc_co_u32_e32 v79, vcc, 0, v27, vcc
	v_add_co_u32_e32 v80, vcc, s0, v26
	s_mov_b32 s0, 0x1080000
	s_nop 0
	v_addc_co_u32_e32 v81, vcc, 0, v27, vcc
	v_add_co_u32_e32 v82, vcc, s0, v26
	s_mov_b32 s0, 0x1200000
	s_nop 0
	v_addc_co_u32_e32 v83, vcc, 0, v27, vcc
	v_add_co_u32_e32 v84, vcc, s0, v26
	s_mov_b32 s0, 0x1380000
	s_nop 0
	v_addc_co_u32_e32 v85, vcc, 0, v27, vcc
	v_add_co_u32_e32 v86, vcc, s0, v26
	s_mov_b32 s0, 0x1500000
	s_nop 0
	v_addc_co_u32_e32 v87, vcc, 0, v27, vcc
	v_add_co_u32_e32 v88, vcc, s0, v26
	v_or_b32_e32 v68, 0x300000, v64
	s_nop 0
	v_addc_co_u32_e32 v89, vcc, 0, v27, vcc
	s_mov_b32 s0, 0x1680000
	v_lshlrev_b32_e32 v70, 2, v68
	v_add_co_u32_e32 v90, vcc, s0, v26
	global_load_dwordx4 v[0:3], v[26:27], off nt
	global_load_dwordx4 v[4:7], v[8:9], off nt
	s_nop 0
	global_load_dwordx4 v[8:11], v[16:17], off nt
	global_load_dwordx4 v[12:15], v[18:19], off nt
	s_nop 0
	global_load_dwordx4 v[16:19], v[28:29], off nt
	global_load_dwordx4 v[20:23], v[30:31], off nt
	v_lshl_add_u64 v[76:77], v[24:25], 0, v[70:71]
	v_addc_co_u32_e32 v91, vcc, 0, v27, vcc
	global_load_dwordx4 v[24:27], v[72:73], off nt
	global_load_dwordx4 v[28:31], v[74:75], off nt
	global_load_dwordx4 v[32:35], v[76:77], off nt
	global_load_dwordx4 v[36:39], v[78:79], off nt
	global_load_dwordx4 v[40:43], v[80:81], off nt
	global_load_dwordx4 v[44:47], v[82:83], off nt
	global_load_dwordx4 v[48:51], v[84:85], off nt
	global_load_dwordx4 v[52:55], v[86:87], off nt
	global_load_dwordx4 v[56:59], v[88:89], off nt
	global_load_dwordx4 v[60:63], v[90:91], off nt
	v_mov_b32_e32 v97, v71
	v_add_u32_e32 v65, 0xfffffe00, v208
	s_mov_b64 s[10:11], 0
	s_mov_b64 s[18:19], 0x800
	s_movk_i32 s5, 0x1dff
	v_add_u32_e32 v67, 0, v96
	v_lshl_add_u64 v[70:71], s[6:7], 0, v[96:97]
; __device__ __forceinline__ void phase0(const Params& p, LAS unsigned char* lds, int tid, int lane, int wave) {
;     ...
;         for (int i = tid; i < 8192; i += 512) { const float v = p.c[i]; vecs[i] = v / (1.f + __expf(-v)); }
.LBB0_21:
	s_waitcnt vmcnt(31)
	v_mul_f32_e32 v72, 0xbfb8aa3b, v120
	v_exp_f32_e32 v72, v72
	s_nop 0
	v_add_f32_e32 v72, 1.0, v72
	v_div_scale_f32 v73, s[6:7], v72, v72, v120
	v_rcp_f32_e32 v74, v73
	v_div_scale_f32 v75, vcc, v120, v72, v120
	v_fma_f32 v76, -v73, v74, 1.0
	v_fmac_f32_e32 v74, v76, v74
	v_mul_f32_e32 v76, v75, v74
	v_fma_f32 v77, -v73, v76, v75
	v_fmac_f32_e32 v76, v77, v74
	v_fma_f32 v73, -v73, v76, v75
	v_div_fmas_f32 v73, v73, v74, v76
	v_div_fixup_f32 v69, v73, v72, v120
	ds_write_b32 v67, v69
	s_waitcnt vmcnt(30)
	v_mul_f32_e32 v72, 0xbfb8aa3b, v121
	v_exp_f32_e32 v72, v72
	s_nop 0
	v_add_f32_e32 v72, 1.0, v72
	v_div_scale_f32 v73, s[6:7], v72, v72, v121
	v_rcp_f32_e32 v74, v73
	v_div_scale_f32 v75, vcc, v121, v72, v121
	v_fma_f32 v76, -v73, v74, 1.0
	v_fmac_f32_e32 v74, v76, v74
	v_mul_f32_e32 v76, v75, v74
	v_fma_f32 v77, -v73, v76, v75
	v_fmac_f32_e32 v76, v77, v74
	v_fma_f32 v73, -v73, v76, v75
	v_div_fmas_f32 v73, v73, v74, v76
	v_div_fixup_f32 v69, v73, v72, v121
	ds_write_b32 v67, v69 offset:2048
	s_waitcnt vmcnt(29)
	v_mul_f32_e32 v72, 0xbfb8aa3b, v122
	v_exp_f32_e32 v72, v72
	s_nop 0
	v_add_f32_e32 v72, 1.0, v72
	v_div_scale_f32 v73, s[6:7], v72, v72, v122
	v_rcp_f32_e32 v74, v73
	v_div_scale_f32 v75, vcc, v122, v72, v122
	v_fma_f32 v76, -v73, v74, 1.0
	v_fmac_f32_e32 v74, v76, v74
	v_mul_f32_e32 v76, v75, v74
	v_fma_f32 v77, -v73, v76, v75
	v_fmac_f32_e32 v76, v77, v74
	v_fma_f32 v73, -v73, v76, v75
	v_div_fmas_f32 v73, v73, v74, v76
	v_div_fixup_f32 v69, v73, v72, v122
	ds_write_b32 v67, v69 offset:4096
	s_waitcnt vmcnt(28)
	v_mul_f32_e32 v72, 0xbfb8aa3b, v123
	v_exp_f32_e32 v72, v72
	s_nop 0
	v_add_f32_e32 v72, 1.0, v72
	v_div_scale_f32 v73, s[6:7], v72, v72, v123
	v_rcp_f32_e32 v74, v73
	v_div_scale_f32 v75, vcc, v123, v72, v123
	v_fma_f32 v76, -v73, v74, 1.0
	v_fmac_f32_e32 v74, v76, v74
	v_mul_f32_e32 v76, v75, v74
	v_fma_f32 v77, -v73, v76, v75
	v_fmac_f32_e32 v76, v77, v74
	v_fma_f32 v73, -v73, v76, v75
	v_div_fmas_f32 v73, v73, v74, v76
	v_div_fixup_f32 v69, v73, v72, v123
	ds_write_b32 v67, v69 offset:6144
	s_waitcnt vmcnt(27)
	v_mul_f32_e32 v72, 0xbfb8aa3b, v124
	v_exp_f32_e32 v72, v72
	s_nop 0
	v_add_f32_e32 v72, 1.0, v72
	v_div_scale_f32 v73, s[6:7], v72, v72, v124
	v_rcp_f32_e32 v74, v73
	v_div_scale_f32 v75, vcc, v124, v72, v124
	v_fma_f32 v76, -v73, v74, 1.0
	v_fmac_f32_e32 v74, v76, v74
	v_mul_f32_e32 v76, v75, v74
	v_fma_f32 v77, -v73, v76, v75
	v_fmac_f32_e32 v76, v77, v74
	v_fma_f32 v73, -v73, v76, v75
	v_div_fmas_f32 v73, v73, v74, v76
	v_div_fixup_f32 v69, v73, v72, v124
	ds_write_b32 v67, v69 offset:8192
	s_waitcnt vmcnt(26)
	v_mul_f32_e32 v72, 0xbfb8aa3b, v125
	v_exp_f32_e32 v72, v72
	s_nop 0
	v_add_f32_e32 v72, 1.0, v72
	v_div_scale_f32 v73, s[6:7], v72, v72, v125
	v_rcp_f32_e32 v74, v73
	v_div_scale_f32 v75, vcc, v125, v72, v125
	v_fma_f32 v76, -v73, v74, 1.0
	v_fmac_f32_e32 v74, v76, v74
	v_mul_f32_e32 v76, v75, v74
	v_fma_f32 v77, -v73, v76, v75
	v_fmac_f32_e32 v76, v77, v74
	v_fma_f32 v73, -v73, v76, v75
	v_div_fmas_f32 v73, v73, v74, v76
	v_div_fixup_f32 v69, v73, v72, v125
	ds_write_b32 v67, v69 offset:10240
	s_waitcnt vmcnt(25)
	v_mul_f32_e32 v72, 0xbfb8aa3b, v126
	v_exp_f32_e32 v72, v72
	s_nop 0
	v_add_f32_e32 v72, 1.0, v72
	v_div_scale_f32 v73, s[6:7], v72, v72, v126
	v_rcp_f32_e32 v74, v73
	v_div_scale_f32 v75, vcc, v126, v72, v126
	v_fma_f32 v76, -v73, v74, 1.0
	v_fmac_f32_e32 v74, v76, v74
	v_mul_f32_e32 v76, v75, v74
	v_fma_f32 v77, -v73, v76, v75
	v_fmac_f32_e32 v76, v77, v74
	v_fma_f32 v73, -v73, v76, v75
	v_div_fmas_f32 v73, v73, v74, v76
	v_div_fixup_f32 v69, v73, v72, v126
	ds_write_b32 v67, v69 offset:12288
	s_waitcnt vmcnt(24)
	v_mul_f32_e32 v72, 0xbfb8aa3b, v127
	v_exp_f32_e32 v72, v72
	s_nop 0
	v_add_f32_e32 v72, 1.0, v72
	v_div_scale_f32 v73, s[6:7], v72, v72, v127
	v_rcp_f32_e32 v74, v73
	v_div_scale_f32 v75, vcc, v127, v72, v127
	v_fma_f32 v76, -v73, v74, 1.0
	v_fmac_f32_e32 v74, v76, v74
	v_mul_f32_e32 v76, v75, v74
	v_fma_f32 v77, -v73, v76, v75
	v_fmac_f32_e32 v76, v77, v74
	v_fma_f32 v73, -v73, v76, v75
	v_div_fmas_f32 v73, v73, v74, v76
	v_div_fixup_f32 v69, v73, v72, v127
	ds_write_b32 v67, v69 offset:14336
	s_waitcnt vmcnt(23)
	v_mul_f32_e32 v72, 0xbfb8aa3b, v128
	v_exp_f32_e32 v72, v72
	s_nop 0
	v_add_f32_e32 v72, 1.0, v72
	v_div_scale_f32 v73, s[6:7], v72, v72, v128
	v_rcp_f32_e32 v74, v73
	v_div_scale_f32 v75, vcc, v128, v72, v128
	v_fma_f32 v76, -v73, v74, 1.0
	v_fmac_f32_e32 v74, v76, v74
	v_mul_f32_e32 v76, v75, v74
	v_fma_f32 v77, -v73, v76, v75
	v_fmac_f32_e32 v76, v77, v74
	v_fma_f32 v73, -v73, v76, v75
	v_div_fmas_f32 v73, v73, v74, v76
	v_div_fixup_f32 v69, v73, v72, v128
	ds_write_b32 v67, v69 offset:16384
	s_waitcnt vmcnt(22)
; __device__ __forceinline__ void phase0(const Params& p, LAS unsigned char* lds, int tid, int lane, int wave) {
;     ...
;         for (int i = tid; i < 8192; i += 512) { const float v = p.c[i]; vecs[i] = v / (1.f + __expf(-v)); }
;         __syncthreads();
;         for (int it = blockIdx.x; it < 192; it += ngemv) { if (it != (int)blockIdx.x) gemv_load(p.w_ada, NMOD, 32 * it, wv, tid); gemv_item(wv, NMOD, 32 * it, p.b_ada, vecs, red, mod, tid); }
	v_mul_f32_e32 v72, 0xbfb8aa3b, v129
	v_exp_f32_e32 v72, v72
	s_nop 0
	v_add_f32_e32 v72, 1.0, v72
	v_div_scale_f32 v73, s[6:7], v72, v72, v129
	v_rcp_f32_e32 v74, v73
	v_div_scale_f32 v75, vcc, v129, v72, v129
	v_fma_f32 v76, -v73, v74, 1.0
	v_fmac_f32_e32 v74, v76, v74
	v_mul_f32_e32 v76, v75, v74
	v_fma_f32 v77, -v73, v76, v75
	v_fmac_f32_e32 v76, v77, v74
	v_fma_f32 v73, -v73, v76, v75
	v_div_fmas_f32 v73, v73, v74, v76
	v_div_fixup_f32 v69, v73, v72, v129
	ds_write_b32 v67, v69 offset:18432
	s_waitcnt vmcnt(21)
	v_mul_f32_e32 v72, 0xbfb8aa3b, v130
	v_exp_f32_e32 v72, v72
	s_nop 0
	v_add_f32_e32 v72, 1.0, v72
	v_div_scale_f32 v73, s[6:7], v72, v72, v130
	v_rcp_f32_e32 v74, v73
	v_div_scale_f32 v75, vcc, v130, v72, v130
	v_fma_f32 v76, -v73, v74, 1.0
	v_fmac_f32_e32 v74, v76, v74
	v_mul_f32_e32 v76, v75, v74
	v_fma_f32 v77, -v73, v76, v75
	v_fmac_f32_e32 v76, v77, v74
	v_fma_f32 v73, -v73, v76, v75
	v_div_fmas_f32 v73, v73, v74, v76
	v_div_fixup_f32 v69, v73, v72, v130
	ds_write_b32 v67, v69 offset:20480
	s_waitcnt vmcnt(20)
	v_mul_f32_e32 v72, 0xbfb8aa3b, v131
	v_exp_f32_e32 v72, v72
	s_nop 0
	v_add_f32_e32 v72, 1.0, v72
	v_div_scale_f32 v73, s[6:7], v72, v72, v131
	v_rcp_f32_e32 v74, v73
	v_div_scale_f32 v75, vcc, v131, v72, v131
	v_fma_f32 v76, -v73, v74, 1.0
	v_fmac_f32_e32 v74, v76, v74
	v_mul_f32_e32 v76, v75, v74
	v_fma_f32 v77, -v73, v76, v75
	v_fmac_f32_e32 v76, v77, v74
	v_fma_f32 v73, -v73, v76, v75
	v_div_fmas_f32 v73, v73, v74, v76
	v_div_fixup_f32 v69, v73, v72, v131
	ds_write_b32 v67, v69 offset:22528
	s_waitcnt vmcnt(19)
	v_mul_f32_e32 v72, 0xbfb8aa3b, v132
	v_exp_f32_e32 v72, v72
	s_nop 0
	v_add_f32_e32 v72, 1.0, v72
	v_div_scale_f32 v73, s[6:7], v72, v72, v132
	v_rcp_f32_e32 v74, v73
	v_div_scale_f32 v75, vcc, v132, v72, v132
	v_fma_f32 v76, -v73, v74, 1.0
	v_fmac_f32_e32 v74, v76, v74
	v_mul_f32_e32 v76, v75, v74
	v_fma_f32 v77, -v73, v76, v75
	v_fmac_f32_e32 v76, v77, v74
	v_fma_f32 v73, -v73, v76, v75
	v_div_fmas_f32 v73, v73, v74, v76
	v_div_fixup_f32 v69, v73, v72, v132
	ds_write_b32 v67, v69 offset:24576
	s_waitcnt vmcnt(18)
	v_mul_f32_e32 v72, 0xbfb8aa3b, v133
	v_exp_f32_e32 v72, v72
	s_nop 0
	v_add_f32_e32 v72, 1.0, v72
	v_div_scale_f32 v73, s[6:7], v72, v72, v133
	v_rcp_f32_e32 v74, v73
	v_div_scale_f32 v75, vcc, v133, v72, v133
	v_fma_f32 v76, -v73, v74, 1.0
	v_fmac_f32_e32 v74, v76, v74
	v_mul_f32_e32 v76, v75, v74
	v_fma_f32 v77, -v73, v76, v75
	v_fmac_f32_e32 v76, v77, v74
	v_fma_f32 v73, -v73, v76, v75
	v_div_fmas_f32 v73, v73, v74, v76
	v_div_fixup_f32 v69, v73, v72, v133
	ds_write_b32 v67, v69 offset:26624
	s_waitcnt vmcnt(17)
	v_mul_f32_e32 v72, 0xbfb8aa3b, v134
	v_exp_f32_e32 v72, v72
	s_nop 0
	v_add_f32_e32 v72, 1.0, v72
	v_div_scale_f32 v73, s[6:7], v72, v72, v134
	v_rcp_f32_e32 v74, v73
	v_div_scale_f32 v75, vcc, v134, v72, v134
	v_fma_f32 v76, -v73, v74, 1.0
	v_fmac_f32_e32 v74, v76, v74
	v_mul_f32_e32 v76, v75, v74
	v_fma_f32 v77, -v73, v76, v75
	v_fmac_f32_e32 v76, v77, v74
	v_fma_f32 v73, -v73, v76, v75
	v_div_fmas_f32 v73, v73, v74, v76
	v_div_fixup_f32 v69, v73, v72, v134
	ds_write_b32 v67, v69 offset:28672
	s_waitcnt vmcnt(16)
	v_mul_f32_e32 v72, 0xbfb8aa3b, v135
	v_exp_f32_e32 v72, v72
	s_nop 0
	v_add_f32_e32 v72, 1.0, v72
	v_div_scale_f32 v73, s[6:7], v72, v72, v135
	v_rcp_f32_e32 v74, v73
	v_div_scale_f32 v75, vcc, v135, v72, v135
	v_fma_f32 v76, -v73, v74, 1.0
	v_fmac_f32_e32 v74, v76, v74
	v_mul_f32_e32 v76, v75, v74
	v_fma_f32 v77, -v73, v76, v75
	v_fmac_f32_e32 v76, v77, v74
	v_fma_f32 v73, -v73, v76, v75
	v_div_fmas_f32 v73, v73, v74, v76
	v_div_fixup_f32 v69, v73, v72, v135
	ds_write_b32 v67, v69 offset:30720
	s_waitcnt vmcnt(0)
	s_or_b64 exec, exec, s[10:11]
	v_lshlrev_b32_e32 v67, 7, v208
	v_and_b32_e32 v69, 0x1fc00, v67
	v_or_b32_e32 v72, 0x380, v67
	v_lshrrev_b32_e32 v67, 5, v208
	v_mul_u32_u24_e32 v67, 0x1800, v67
	v_and_b32_e32 v89, 31, v208
	v_lshlrev_b32_e32 v80, 2, v67
	v_mov_b32_e32 v81, 0
	v_lshlrev_b32_e32 v66, 2, v66
	s_movk_i32 s0, 0x380
	v_lshl_add_u64 v[70:71], s[16:17], 0, v[80:81]
	v_lshlrev_b32_e32 v80, 2, v89
	v_mov_b32_e32 v67, v81
	v_add_u32_e32 v65, 0, v66
	v_lshl_add_u64 v[84:85], s[14:15], 0, v[66:67]
	v_and_or_b32 v66, v96, s0, v80
	s_movk_i32 s1, 0x100
	s_cmp_lg_u64 s[12:13], 0
	v_add_u32_e32 v66, 0, v66
	s_mov_b32 s11, 0
	v_lshl_add_u32 v88, v174, 2, 0
	v_cmp_gt_u32_e64 s[6:7], s1, v208
	v_lshl_add_u64 v[82:83], v[70:71], 0, v[80:81]
	s_cselect_b64 s[14:15], -1, 0
	v_add_u32_e32 v90, 0x8000, v66
	v_lshlrev_b32_e32 v80, 2, v64
	v_lshlrev_b32_e32 v86, 2, v68
	v_add_u32_e32 v91, v65, v69
	v_add_u32_e32 v92, v65, v72
	s_mov_b32 s5, s2
	s_waitcnt lgkmcnt(0)
	s_barrier
	s_branch .LBB0_25
